# attention on XCDs 0-3 and scan on XCDs 4-7 (split by blockIdx%8 instead of blockIdx/8)
# speedup vs baseline: 1.0412x; 1.0058x over previous
; __device__ __forceinline__ int bid_() { int b = blockIdx.x; asm volatile("" : "+s"(b)); return b; }
; __device__ __forceinline__ void phase_scan(CParams& P, LAS unsigned char* lds) {
;     ...
;     const int bx_ = bid_(); const int vcu_ = (nb_ % 8 == 0) ? (bx_ % 8) * (nb_ / 8) + bx_ / 8 : bx_;
;     for (int task = vcu_; task < GSEQ * 8 * 2 * 2; task += nb_) {
;         const int rowhalf = task & 1, dir = (task >> 1) & 1, h = (task >> 2) & 7, s = task >> 5;
;         float* OUT = (float*)(P.ws + WS_P2) + (size_t)dir * TG * 512;
;         __syncthreads();
;         if (wid >= 4) {
;             const int ltid = tid - 256; f16x8 v[6];
;     ...
;             SC_GLOAD(0); SC_WRITE(0); SC_GLOAD(1);
; #pragma unroll 1
;             for (int c = 0; c < NCH; ++c) {
;                 __syncthreads();
;                 if (c + 1 < NCH) { SC_WRITE(c + 1); if (c + 2 < NCH) SC_GLOAD(c + 2); }
;             }
;             __syncthreads();
;     ...
;         } else {
;             const int rl = lane >> 3, oct = lane & 7, rloc = wid * 8 + rl;
;             __builtin_amdgcn_s_setprio(3);
;             f32x4 s0 = {0.f, 0.f, 0.f, 0.f}, s1 = {0.f, 0.f, 0.f, 0.f};
;             float* op = OUT + ((size_t)s * SEQ + (dir ? SEQ - 1 : 0)) * 512 + h * 64 + rowhalf * 32 + rloc; const long ostep = dir ? -512 : 512;
.Lr3_scan:
	s_waitcnt vmcnt(0)
	s_and_b32 s4, s2, 7
	s_add_i32 s4, s4, -4
	s_lshl_b32 s4, s4, 5
	s_lshr_b32 s5, s2, 3
	s_add_i32 s4, s4, s5
	s_lshr_b32 s7, s4, 4
	s_and_b32 s5, s4, 1
	s_bfe_u32 s6, s4, 0x30001
	s_mul_i32 s9, s7, 0xc00000
	s_mul_i32 s12, s6, 0x180
	s_add_i32 s9, s9, s12
	s_add_i32 s12, s9, 0x1a000000
	s_add_u32 s40, s22, s12
	s_addc_u32 s41, s23, 0
	s_mul_i32 s12, s5, 0x6000000
	s_add_i32 s12, s12, s9
	s_add_i32 s12, s12, 0x20000000
	s_add_u32 s42, s22, s12
	s_addc_u32 s43, s23, 0
	s_lshl_b32 s12, s7, 22
	s_lshl_b32 s15, s6, 7
	s_add_i32 s12, s12, s15
	s_add_i32 s12, s12, 0x2e000000
	s_add_u32 s44, s22, s12
	s_addc_u32 s45, s23, 0
	s_lshl_b32 s12, s7, 23
	s_lshl_b32 s15, s6, 8
	s_add_i32 s12, s12, s15
	s_lshl_b32 s15, s5, 26
	s_add_i32 s12, s12, s15
	s_add_i32 s12, s12, 0x8000000
	s_add_u32 s10, s22, s12
	s_addc_u32 s11, s23, 0
	s_cmp_eq_u32 s5, 0
	s_cselect_b32 s46, 0, 0xfff
	s_mov_b32 s47, 0xfffe8000
	s_cselect_b32 s48, 0x18000, s47
	s_cselect_b32 s49, 0, -1
	s_mov_b32 s47, 0xffff8000
	s_cselect_b32 s36, 0x8000, s47
	s_cselect_b32 s37, 0, -1
	s_mov_b32 s47, 0xffffe000
	s_cselect_b32 s13, 0x2000, s47
	s_mov_b32 s50, 0xaaaaaaaa
	s_mov_b32 s51, 0xaaaaaaaa
	s_mov_b32 s52, 0xcccccccc
	s_mov_b32 s53, 0xcccccccc
	v_lshrrev_b32_e32 v0, 6, v222
	v_and_b32_e32 v6, 15, v222
	v_readfirstlane_b32 s28, v0
	v_lshrrev_b32_e32 v7, 4, v222
	s_cmp_lt_u32 s28, 4
	s_cselect_b32 s36, s48, s36
	s_cselect_b32 s37, s49, s37
	v_xor_b32_e32 v1, s46, v7
	v_mul_u32_u24_e32 v1, 0xc00, v1
	v_lshlrev_b32_e32 v64, 4, v6
	v_add_u32_e32 v130, v1, v64
	v_mov_b32_e32 v131, 0
	v_and_b32_e32 v1, 8, v6
	v_lshlrev_b32_e32 v1, 4, v1
	v_add_u32_e32 v128, v130, v1
	v_mov_b32_e32 v129, 0
	v_lshl_add_u64 v[152:153], s[40:41], 0, v[128:129]
	v_lshl_add_u64 v[154:155], s[42:43], 0, v[130:131]
	v_mul_u32_u24_e32 v0, 0x500, v7
	v_and_b32_e32 v1, 7, v6
	v_lshlrev_b32_e32 v1, 5, v1
	v_add_u32_e32 v0, v0, v1
	v_and_b32_e32 v1, 8, v6
	v_lshlrev_b32_e32 v127, 7, v1
	v_sub_u32_e32 v127, 0x400, v127
	v_add_u32_e32 v178, v0, v127
	v_lshlrev_b32_e32 v127, 5, v1
	v_add_u32_e32 v127, 0x100, v127
	v_add_u32_e32 v179, v0, v127
	v_lshrrev_b32_e32 v0, 3, v222
	v_and_b32_e32 v0, 31, v0
	v_and_b32_e32 v1, 7, v222
	v_xor_b32_e32 v127, s46, v0
	s_cmp_lt_u32 s28, 4
	s_cbranch_scc0 .Lr3_roleV
	v_mul_u32_u24_e32 v127, 0xc00, v127
	v_lshlrev_b32_e32 v128, 4, v1
	v_add_u32_e32 v128, v127, v128
	v_add_u32_e32 v128, 0x100, v128
	v_mov_b32_e32 v129, 0
	v_lshl_add_u64 v[156:157], s[42:43], 0, v[128:129]
	v_mul_u32_u24_e32 v0, 0x500, v0
	v_lshlrev_b32_e32 v1, 5, v1
	v_add_u32_e32 v0, v0, v1
	v_add_u32_e32 v180, 0x300, v0
	s_branch .Lr3_roleDone

; __device__ __forceinline__ int bid_() { int b = blockIdx.x; asm volatile("" : "+s"(b)); return b; }
; __device__ __forceinline__ int nblk_() { int g = gridDim.x; asm volatile("" : "+s"(g)); return g; }
; __device__ __forceinline__ void phase_attn(CParams& P, LAS unsigned char* lds) {
;     ...
;     const int G = nblk_(), bx = bid_(); const int vcu = (G % 8 == 0) ? (bx % 8) * (G / 8) + bx / 8 : bx;
;     constexpr int KROW = 208, VROW = 272, KBUF = 128 * KROW, VBUF = 64 * VROW, VOFF = 2 * KBUF, NT = SEQ / 128;
;     static_assert(VOFF + 2 * VBUF <= 131072, "attention LDS map");
;     const int kr0 = tid / 12, kc0 = tid % 12, kr1 = (512 + tid) / 12, kc1 = (512 + tid) % 12, kr2 = (1024 + tid) / 12, kc2 = (1024 + tid) % 12, vr0 = tid >> 4, vc0 = tid & 15, vr1 = 32 + vr0, vgo = (vc0 >> 1) * 32 + (vc0 & 1) * 8;
;     ...
;     for (int u = vcu; u < GSEQ * 8 * 16; u += G) {
;         const int sh = u >> 4, qb = u & 15, s = sh >> 3, h = sh & 7; const size_t tok0 = (size_t)s * SEQ;
;         bf16x8 qf[6]; { const bf16_t* qp = Q + (tok0 + qb * 256 + wid * 32 + ql) * 768 + h * 96 + 8 * hi;
; #pragma unroll
;             for (int ds = 0; ds < 6; ++ds) qf[ds] = *(const bf16x8*)(qp + 16 * ds); }
;         const bf16_t* kg0 = KF + (tok0 + kr0) * 768 + h * 96 + kc0 * 8; const bf16_t* kg1 = KF + (tok0 + kr1) * 768 + h * 96 + kc1 * 8; const bf16_t* kg2 = KF + (tok0 + kr2) * 768 + h * 96 + kc2 * 8;
;         const bf16_t* vg0 = VT + ((size_t)(s * 8 + h) * 64 + vr0) * SEQ + vc0 * 8; const bf16_t* vg1 = vg0 + (size_t)32 * SEQ;
.LBB0_606:
	s_and_b64 vcc, exec, s[4:5]
	s_cbranch_vccz .LBB0_627
	s_and_b32 s4, s2, 7
	s_cmp_ge_u32 s4, 4
	s_cbranch_scc1 .Lr3_scan
	s_waitcnt vmcnt(0)
	v_mov_b32_e32 v0, v222
	s_load_dword s10, s[80:81], 0x0
	s_waitcnt lgkmcnt(0)
	s_and_b32 s4, s10, 7
	s_mov_b32 s11, s2
	s_cmp_lg_u32 s4, 0
	s_cbranch_scc1 .LBB0_609
	s_ashr_i32 s5, s11, 31
	s_lshr_b32 s5, s5, 29
	s_add_i32 s5, s11, s5
	s_ashr_i32 s6, s5, 3
	s_and_b32 s5, s5, -8
	s_ashr_i32 s4, s10, 3
	s_sub_i32 s5, s11, s5
	s_mul_i32 s4, s5, s4
	s_add_i32 s11, s4, s6
.LBB0_609:
	s_movk_i32 s10, 0x80
	s_cmpk_gt_i32 s11, 0x3ff
	s_cbranch_scc1 .LBB0_626
	v_add_u32_e32 v3, 0x400, v0
	v_mul_hi_i32 v4, v3, s84
	v_lshrrev_b32_e32 v5, 31, v4
	v_ashrrev_i32_e32 v4, 1, v4
	v_add_u32_e32 v158, v4, v5
	v_mul_lo_u32 v4, v158, 12
	v_sub_u32_e32 v10, v3, v4
	v_add_u32_e32 v3, 0x200, v0
	v_mul_hi_i32 v4, v3, s84
	v_lshrrev_b32_e32 v5, 31, v4
	v_ashrrev_i32_e32 v4, 1, v4
	v_add_u32_e32 v160, v4, v5
	v_mul_lo_u32 v4, v160, 12
	v_sub_u32_e32 v11, v3, v4
	v_mul_hi_i32 v3, v0, s84
	v_lshlrev_b32_e32 v2, 3, v0
	v_lshrrev_b32_e32 v4, 31, v3
	v_ashrrev_i32_e32 v3, 1, v3
	v_lshlrev_b32_e32 v1, 4, v0
	v_and_b32_e32 v2, 8, v2
	s_movk_i32 s4, 0xe0
	v_add_u32_e32 v162, v3, v4
	v_and_or_b32 v195, v1, s4, v2
	v_ashrrev_i32_e32 v2, 4, v0
	v_mul_lo_u32 v3, v162, 12
	v_sub_u32_e32 v12, v0, v3
	v_ashrrev_i32_e32 v3, 31, v2
	s_add_u32 s40, s22, 0x34000000
	v_lshlrev_b64 v[4:5], 13, v[2:3]
	v_and_b32_e32 v64, 0xf0, v1
	s_addc_u32 s41, s23, 0
	v_lshl_add_u64 v[6:7], s[22:23], 0, v[4:5]
	s_add_u32 s42, s22, 0x37000000
	v_lshl_add_u64 v[6:7], v[6:7], 0, v[64:65]
	s_mov_b64 s[4:5], 0x3a000000
	s_addc_u32 s43, s23, 0
	v_lshl_add_u64 v[172:173], v[6:7], 0, s[4:5]
	s_movk_i32 s4, 0xd0
	s_add_u32 s44, s22, 0x3c000000
	v_lshlrev_b32_e32 v170, 3, v10
	v_mul_lo_u32 v196, v162, s4
	v_mul_lo_u32 v198, v160, s4
	v_mul_lo_u32 v200, v158, s4
	s_movk_i32 s4, 0x110
	v_or_b32_e32 v4, v4, v64
	s_addc_u32 s45, s23, 0
	v_ashrrev_i32_e32 v171, 31, v170
	v_mul_lo_u32 v202, v2, s4
	v_lshl_add_u64 v[4:5], s[22:23], 0, v[4:5]
	s_mov_b64 s[4:5], 0x3a040100
	v_lshlrev_b32_e32 v168, 3, v11
	v_lshl_add_u64 v[174:175], v[4:5], 0, s[4:5]
	s_add_u32 s4, s22, 0x37030000
	v_lshlrev_b64 v[4:5], 1, v[170:171]
	s_movk_i32 s8, 0x600
	v_ashrrev_i32_e32 v169, 31, v168
	s_addc_u32 s5, s23, 0
	v_mad_i64_i32 v[4:5], s[6:7], v158, s8, v[4:5]
	v_lshlrev_b32_e32 v166, 3, v12
	v_lshl_add_u64 v[176:177], s[4:5], 0, v[4:5]
	v_lshlrev_b64 v[4:5], 1, v[168:169]
	v_and_b32_e32 v1, 31, v0
	v_bfe_u32 v8, v0, 5, 1
	v_ashrrev_i32_e32 v0, 1, v0
	v_ashrrev_i32_e32 v167, 31, v166
	v_mad_i64_i32 v[4:5], s[6:7], v160, s8, v[4:5]
	v_and_b32_e32 v0, 0xffffffe0, v0
	v_lshlrev_b32_e32 v199, 4, v11
	v_lshlrev_b32_e32 v201, 4, v10
	v_mul_u32_u24_e32 v10, 0xd0, v1
	v_lshlrev_b32_e32 v11, 4, v8
	v_lshl_add_u64 v[178:179], s[4:5], 0, v[4:5]
	v_lshlrev_b64 v[4:5], 1, v[166:167]
	v_add_u32_e32 v9, 0, v195
	v_ashrrev_i32_e32 v165, 31, v0
	v_or_b32_e32 v164, v0, v1
	v_lshlrev_b32_e32 v0, 3, v8
	v_add_u32_e32 v3, 0, v196
	v_lshlrev_b32_e32 v197, 4, v12
	v_add_u32_e32 v6, 0, v198
	v_add_u32_e32 v7, 0, v200
	v_lshlrev_b32_e32 v2, 2, v8
	v_add3_u32 v203, 0, v10, v11
	v_mad_i64_i32 v[4:5], s[6:7], v162, s8, v[4:5]
	v_ashrrev_i32_e32 v163, 31, v162
	v_ashrrev_i32_e32 v161, 31, v160
	v_ashrrev_i32_e32 v159, 31, v158
	v_lshl_add_u32 v204, v1, 6, v203
	v_lshl_add_u64 v[180:181], s[4:5], 0, v[4:5]
	v_lshlrev_b32_e32 v64, 1, v0
	v_add_u32_e32 v205, v3, v197
	v_add_u32_e32 v206, v6, v199
	v_add_u32_e32 v207, v7, v201
	v_add_u32_e32 v208, v9, v202
	v_lshlrev_b32_e32 v182, 1, v2
	s_branch .LBB0_612
